# ffn_up K-loop DMA split three, three and two pieces behind the first three fragment-read groups (other loops four and four)
# baseline (speedup 1.0000x reference)
; #define MFMA16(a, b, c) __builtin_amdgcn_mfma_f32_16x16x32_bf16((a), (b), (c), 0, 0, 0)
; template <int AMODE, bool SWAPO = true>
; DI void mainloop_dma16(f32x4 (&acc)[4][2][2][2], const TD& c, const TD& n, bool hasn, bool primed, int& s, int tid) {
;     ...
; #pragma unroll
;         for (int k2 = 0; k2 < 2; ++k2) {
;             const int co = ((4 * k2 + q) ^ key) << 4;
;             bf16x8 fw[2][2];
; #pragma unroll
;             for (int ni = 0; ni < 2; ++ni)
; #pragma unroll
;                 for (int rh = 0; rh < 2; ++rh) fw[ni][rh] = *(const bf16x8*)(sb + b_off + (ni * 32 + rh * 16) * 128 + co);
; #pragma unroll
;             for (int mh = 0; mh < 2; ++mh) {
;                 bf16x8 fx[2][2];
; #pragma unroll
;                 for (int m2 = 0; m2 < 2; ++m2)
; #pragma unroll
;                     for (int ch = 0; ch < 2; ++ch) fx[m2][ch] = *(const bf16x8*)(sb + a_off + ((2 * mh + m2) * 32 + ch * 16) * 128 + co);
;                 asm volatile("" ::: "memory");
;                 if (doload) { const int p0 = (2 * k2 + mh) * 2; piece(c, ao, bo, nkt, ns, p0); piece(c, ao, bo, nkt, ns, p0 + 1); }
;                 asm volatile("" ::: "memory");
; #pragma unroll
;                 for (int m2 = 0; m2 < 2; ++m2)
; #pragma unroll
;                     for (int ni = 0; ni < 2; ++ni)
; #pragma unroll
;                         for (int rh = 0; rh < 2; ++rh)
; #pragma unroll
;                             for (int ch = 0; ch < 2; ++ch)
;                                 acc[2 * mh + m2][ni][rh][ch] = SWAPO ? MFMA16(fw[ni][rh], fx[m2][ch], acc[2 * mh + m2][ni][rh][ch]) : MFMA16(fx[m2][ch], fw[ni][rh], acc[2 * mh + m2][ni][rh][ch]);
;             }
.LBB0_1198:
	s_waitcnt lgkmcnt(0)
	v_mfma_f32_16x16x32_bf16 v[120:123], v[152:155], v[140:143], v[120:123]
	s_andn2_b64 vcc, exec, s[18:19]
	v_mfma_f32_16x16x32_bf16 v[112:115], v[156:159], v[140:143], v[112:115]
	v_mfma_f32_16x16x32_bf16 v[56:59], v[152:155], v[136:139], v[56:59]
	v_mfma_f32_16x16x32_bf16 v[48:51], v[156:159], v[136:139], v[48:51]
	v_mfma_f32_16x16x32_bf16 v[124:127], v[152:155], v[132:135], v[124:127]
	v_mfma_f32_16x16x32_bf16 v[116:119], v[156:159], v[132:135], v[116:119]
	v_mfma_f32_16x16x32_bf16 v[60:63], v[152:155], v[128:131], v[60:63]
	v_mfma_f32_16x16x32_bf16 v[52:55], v[156:159], v[128:131], v[52:55]
	v_mfma_f32_16x16x32_bf16 v[104:107], v[144:147], v[140:143], v[104:107]
	v_mfma_f32_16x16x32_bf16 v[96:99], v[148:151], v[140:143], v[96:99]
	v_mfma_f32_16x16x32_bf16 v[40:43], v[144:147], v[136:139], v[40:43]
	v_mfma_f32_16x16x32_bf16 v[32:35], v[148:151], v[136:139], v[32:35]
	v_mfma_f32_16x16x32_bf16 v[108:111], v[144:147], v[132:135], v[108:111]
	v_mfma_f32_16x16x32_bf16 v[100:103], v[148:151], v[132:135], v[100:103]
	v_mfma_f32_16x16x32_bf16 v[44:47], v[144:147], v[128:131], v[44:47]
	v_mfma_f32_16x16x32_bf16 v[36:39], v[148:151], v[128:131], v[36:39]
	ds_read_b128 v[152:155], v193 offset:8192
	ds_read_b128 v[156:159], v193 offset:10240
	ds_read_b128 v[144:147], v193 offset:12288
	ds_read_b128 v[148:151], v193 offset:14336
	v_cndmask_b32_e64 v193, 0, 1, s[18:19]
	v_cmp_ne_u32_e64 s[0:1], 1, v193
	s_cbranch_vccnz .LBB0_1200
	v_add_u32_e32 v196, 0xc00, v176
	v_lshl_add_u64 v[194:195], v[166:167], 0, s[4:5]
	v_readfirstlane_b32 s18, v196
	s_mov_b32 m0, s18
	s_nop 0
	global_load_lds_dwordx4 v[194:195], off
	v_add_u32_e32 v196, 0x8000, v176
	v_lshl_add_u64 v[194:195], v[168:169], 0, s[4:5]
	v_readfirstlane_b32 s18, v196
	s_mov_b32 m0, s18
	s_nop 0
	global_load_lds_dwordx4 v[194:195], off
	v_add_u32_e32 v196, 0x8400, v176
	v_lshl_add_u64 v[194:195], v[170:171], 0, s[4:5]
	v_readfirstlane_b32 s18, v196
	s_mov_b32 m0, s18
	s_nop 0
	global_load_lds_dwordx4 v[194:195], off
.LBB0_1200:
	s_waitcnt lgkmcnt(0)
	v_mfma_f32_16x16x32_bf16 v[28:31], v[152:155], v[128:131], v[28:31]
	v_add_u32_e32 v191, v191, v190
	s_and_b64 vcc, exec, s[0:1]
	v_mfma_f32_16x16x32_bf16 v[20:23], v[156:159], v[128:131], v[20:23]
	v_mfma_f32_16x16x32_bf16 v[12:15], v[144:147], v[128:131], v[12:15]
	v_mfma_f32_16x16x32_bf16 v[4:7], v[148:151], v[128:131], v[4:7]
	v_add_u32_e32 v128, v192, v190
	v_mfma_f32_16x16x32_bf16 v[88:91], v[152:155], v[140:143], v[88:91]
	v_mfma_f32_16x16x32_bf16 v[80:83], v[156:159], v[140:143], v[80:83]
	v_mfma_f32_16x16x32_bf16 v[24:27], v[152:155], v[136:139], v[24:27]
	v_mfma_f32_16x16x32_bf16 v[16:19], v[156:159], v[136:139], v[16:19]
	v_mfma_f32_16x16x32_bf16 v[92:95], v[152:155], v[132:135], v[92:95]
	v_mfma_f32_16x16x32_bf16 v[84:87], v[156:159], v[132:135], v[84:87]
	v_mfma_f32_16x16x32_bf16 v[72:75], v[144:147], v[140:143], v[72:75]
	v_mfma_f32_16x16x32_bf16 v[64:67], v[148:151], v[140:143], v[64:67]
	v_mfma_f32_16x16x32_bf16 v[8:11], v[144:147], v[136:139], v[8:11]
	v_mfma_f32_16x16x32_bf16 v[0:3], v[148:151], v[136:139], v[0:3]
	v_mfma_f32_16x16x32_bf16 v[76:79], v[144:147], v[132:135], v[76:79]
	ds_read_b128 v[140:143], v128 offset:32768
	ds_read_b128 v[144:147], v128 offset:34816
	ds_read_b128 v[136:139], v128 offset:36864
	ds_read_b128 v[128:131], v128 offset:38912
	v_mfma_f32_16x16x32_bf16 v[68:71], v[148:151], v[132:135], v[68:71]
	ds_read_b128 v[152:155], v191
	ds_read_b128 v[156:159], v191 offset:2048
	ds_read_b128 v[132:135], v191 offset:4096
	ds_read_b128 v[148:151], v191 offset:6144
	s_cbranch_vccnz .LBB0_1202
	v_add_u32_e32 v194, 0x8800, v176
	v_lshl_add_u64 v[192:193], v[172:173], 0, s[4:5]
	v_readfirstlane_b32 s18, v194
	s_mov_b32 m0, s18
	s_nop 0
	global_load_lds_dwordx4 v[192:193], off
	v_add_u32_e32 v194, 0x8c00, v176
	v_lshl_add_u64 v[192:193], v[174:175], 0, s[4:5]
	v_readfirstlane_b32 s18, v194
	s_mov_b32 m0, s18
	s_nop 0
	global_load_lds_dwordx4 v[192:193], off
